# comb6 with 16 bytes of s_nop padding so the GEMM loop heads sit at the same byte phases as in the earlier best builds
# speedup vs baseline: 1.0069x; 1.0020x over previous
.Lser_exit:
	s_nop 0
	s_nop 0
	v_lshlrev_b32_e32 v157, 2, v0
